# indexer threshold search: when a token is exactly one short (count 255) finish it with one max-scan (tau = largest score below the candidate) instead of further bisection
# baseline (speedup 1.0000x reference)
.LBB0_1533:
	s_nop 1
	v_add_u32_dpp v7, v7, v7 quad_perm:[1,0,3,2] row_mask:0xf bank_mask:0xf bound_ctrl:1
	s_nop 1
	v_add_u32_dpp v7, v7, v7 quad_perm:[2,3,0,1] row_mask:0xf bank_mask:0xf bound_ctrl:1
	s_nop 1
	v_add_u32_dpp v7, v7, v7 row_half_mirror row_mask:0xf bank_mask:0xf bound_ctrl:1
	s_nop 1
	v_add_u32_dpp v7, v7, v7 row_mirror row_mask:0xf bank_mask:0xf bound_ctrl:1
	s_nop 1
	v_add_u32_dpp v7, v7, v7 row_bcast:15 row_mask:0xa bank_mask:0xf
	s_nop 0
	v_readlane_b32 s50, v7, 31
	v_readlane_b32 s51, v7, 63
	s_nop 1
	v_mov_b32_e32 v7, s51
	v_mov_b32_e32 v8, s50
	v_cndmask_b32_e64 v8, v7, v8, s[6:7]
	v_cmp_lt_i32_e64 s[82:83], s33, v8
	v_cmp_eq_u32_e64 s[84:85], s33, v8
	v_cvt_f32_i32_e32 v8, v8
	s_andn2_b64 s[84:85], s[84:85], s[72:73]
	s_nop 0
	v_cndmask_b32_e64 v6, v6, v0, s[84:85]
	s_or_b64 s[84:85], s[84:85], s[72:73]
	s_andn2_b64 s[86:87], s[82:83], s[84:85]
	s_or_b64 s[88:89], s[82:83], s[84:85]
	s_andn2_b64 s[88:89], exec, s[88:89]
	v_cndmask_b32_e64 v4, v4, v0, s[86:87]
	v_cndmask_b32_e64 v3, v3, v8, s[86:87]
	v_cndmask_b32_e64 v5, v5, v0, s[88:89]
	v_cndmask_b32_e64 v2, v2, v8, s[88:89]
	s_or_b64 s[78:79], s[78:79], s[86:87]
	s_or_b64 s[76:77], s[76:77], s[88:89]
	s_and_b64 s[90:91], s[78:79], s[76:77]
	v_sub_f32_e32 v9, v3, v2
	v_rcp_f32_e32 v9, v9
	v_add_f32_e32 v10, 0xc3800000, v3
	s_and_b32 s98, s58, 3
	s_cmp_lg_u32 s98, 3
	s_cselect_b64 vcc, -1, 0
	v_mul_f32_e32 v9, v10, v9
	v_max_f32_e32 v9, 0x3ca3d70a, v9
	v_min_f32_e32 v9, 0x3f7ae148, v9
	v_cndmask_b32_e32 v9, 0.5, v9, vcc
	v_sub_f32_e32 v10, v5, v4
	v_fma_f32 v10, v10, v9, v4
	v_mul_f32_e32 v11, 0.5, v5
	v_fmac_f32_e32 v11, 0.5, v4
	v_cmp_ngt_f32_e32 vcc, v10, v4
	v_cmp_nlt_f32_e64 s[98:99], v10, v5
	v_cmp_ngt_f32_e64 s[100:101], v11, v4
	s_or_b64 s[98:99], vcc, s[98:99]
	v_cmp_nlt_f32_e32 vcc, v11, v5
	s_nop 0
	v_cndmask_b32_e64 v10, v10, v11, s[98:99]
	s_or_b64 s[100:101], vcc, s[100:101]
	s_and_b64 s[100:101], s[100:101], s[98:99]
	s_and_b64 s[100:101], s[100:101], s[90:91]
	s_andn2_b64 s[100:101], s[100:101], s[84:85]
	v_cndmask_b32_e64 v11, -v1, v1, s[82:83]
	v_add_f32_e32 v11, v0, v11
	v_cndmask_b32_e64 v10, v11, v10, s[90:91]
	v_add_f32_e32 v11, v1, v1
	s_or_b64 s[98:99], s[90:91], s[84:85]
	s_andn2_b64 s[98:99], exec, s[98:99]
	v_cndmask_b32_e64 v1, v1, v11, s[98:99]
	v_cndmask_b32_e64 v6, v6, v4, s[100:101]
	s_or_b64 s[72:73], s[84:85], s[100:101]
	s_mov_b32 s98, 0x437f0000
	v_cmp_eq_f32_e64 s[82:83], s98, v8
	s_andn2_b64 s[82:83], s[82:83], s[72:73]
	s_cmp_lg_u64 s[82:83], 0
	s_cbranch_scc1 .Lwalk0
.Lwalkret0:
	s_andn2_b64 s[98:99], exec, s[72:73]
	v_cndmask_b32_e64 v0, v0, v10, s[98:99]
	s_cmp_eq_u64 s[98:99], 0
	s_cbranch_scc1 .Ldx0
	s_cmp_eq_u32 s58, 63
	s_cbranch_scc1 .Ldx0
	s_add_i32 s58, s58, 1
	s_branch .LBB0_1521
.Lwalk0:
	v_mov_b32_e32 v100, 0xff800000
	v_mov_b32_e32 v101, 0xff800000
	v_cmp_lt_f32_e64 s[98:99], v201, v0
	v_cmp_lt_f32_e64 s[100:101], v209, v0
	v_cmp_lt_f32_e32 vcc, v200, v0
	v_cndmask_b32_e64 v104, v101, v201, s[98:99]
	v_cmp_lt_f32_e64 s[98:99], v202, v0
	v_max_f32_e32 v100, v100, v104
	v_cndmask_b32_e64 v105, v101, v209, s[100:101]
	v_cmp_lt_f32_e64 s[100:101], v112, v0
	v_max_f32_e32 v100, v100, v105
	v_cndmask_b32_e32 v104, v101, v200, vcc
	v_cmp_lt_f32_e32 vcc, v113, v0
	v_max_f32_e32 v100, v100, v104
	v_cndmask_b32_e64 v105, v101, v202, s[98:99]
	v_cmp_lt_f32_e64 s[98:99], v114, v0
	v_max_f32_e32 v100, v100, v105
	v_cndmask_b32_e64 v104, v101, v112, s[100:101]
	v_cmp_lt_f32_e64 s[100:101], v115, v0
	v_max_f32_e32 v100, v100, v104
	v_cndmask_b32_e32 v105, v101, v113, vcc
	v_cmp_lt_f32_e32 vcc, v116, v0
	v_max_f32_e32 v100, v100, v105
	v_cndmask_b32_e64 v104, v101, v114, s[98:99]
	v_cmp_lt_f32_e64 s[98:99], v117, v0
	v_max_f32_e32 v100, v100, v104
	v_cndmask_b32_e64 v105, v101, v115, s[100:101]
	v_cmp_lt_f32_e64 s[100:101], v118, v0
	v_max_f32_e32 v100, v100, v105
	v_cndmask_b32_e32 v104, v101, v116, vcc
	v_cmp_lt_f32_e32 vcc, v119, v0
	v_max_f32_e32 v100, v100, v104
	v_cndmask_b32_e64 v105, v101, v117, s[98:99]
	v_cmp_lt_f32_e64 s[98:99], v205, v0
	v_max_f32_e32 v100, v100, v105
	v_cndmask_b32_e64 v104, v101, v118, s[100:101]
	v_cmp_lt_f32_e64 s[100:101], v206, v0
	v_max_f32_e32 v100, v100, v104
	v_cndmask_b32_e32 v105, v101, v119, vcc
	v_cmp_lt_f32_e32 vcc, v207, v0
	v_max_f32_e32 v100, v100, v105
	v_cndmask_b32_e64 v104, v101, v205, s[98:99]
	v_cmp_lt_f32_e64 s[98:99], v208, v0
	v_max_f32_e32 v100, v100, v104
	v_cndmask_b32_e64 v105, v101, v206, s[100:101]
	v_cmp_lt_f32_e64 s[100:101], v210, v0
	v_max_f32_e32 v100, v100, v105
	v_cndmask_b32_e32 v104, v101, v207, vcc
	v_cmp_lt_f32_e32 vcc, v212, v0
	v_max_f32_e32 v100, v100, v104
	v_cndmask_b32_e64 v105, v101, v208, s[98:99]
	v_cmp_lt_f32_e64 s[98:99], v214, v0
	v_max_f32_e32 v100, v100, v105
	v_cndmask_b32_e64 v104, v101, v210, s[100:101]
	v_cmp_lt_f32_e64 s[100:101], v217, v0
	v_max_f32_e32 v100, v100, v104
	v_cndmask_b32_e32 v105, v101, v212, vcc
	v_cmp_lt_f32_e32 vcc, v211, v0
	v_max_f32_e32 v100, v100, v105
	v_cndmask_b32_e64 v104, v101, v214, s[98:99]
	v_cmp_lt_f32_e64 s[98:99], v213, v0
	v_max_f32_e32 v100, v100, v104
	v_cndmask_b32_e64 v105, v101, v217, s[100:101]
	v_cmp_lt_f32_e64 s[100:101], v216, v0
	v_max_f32_e32 v100, v100, v105
	v_cndmask_b32_e32 v104, v101, v211, vcc
	v_cmp_lt_f32_e32 vcc, v218, v0
	v_max_f32_e32 v100, v100, v104
	v_cndmask_b32_e64 v105, v101, v213, s[98:99]
	v_cmp_lt_f32_e64 s[98:99], v227, v0
	v_max_f32_e32 v100, v100, v105
	v_cndmask_b32_e64 v104, v101, v216, s[100:101]
	v_cmp_lt_f32_e64 s[100:101], v229, v0
	v_max_f32_e32 v100, v100, v104
	v_cndmask_b32_e32 v105, v101, v218, vcc
	v_cmp_lt_f32_e32 vcc, v231, v0
	v_max_f32_e32 v100, v100, v105
	v_cndmask_b32_e64 v104, v101, v227, s[98:99]
	v_cmp_lt_f32_e64 s[98:99], v233, v0
	v_max_f32_e32 v100, v100, v104
	v_cndmask_b32_e64 v105, v101, v229, s[100:101]
	v_cmp_lt_f32_e64 s[100:101], v228, v0
	v_max_f32_e32 v100, v100, v105
	v_cndmask_b32_e32 v104, v101, v231, vcc
	v_cmp_lt_f32_e32 vcc, v230, v0
	v_max_f32_e32 v100, v100, v104
	v_cndmask_b32_e64 v105, v101, v233, s[98:99]
	v_cmp_lt_f32_e64 s[98:99], v232, v0
	v_max_f32_e32 v100, v100, v105
	v_cndmask_b32_e64 v104, v101, v228, s[100:101]
	v_cmp_lt_f32_e64 s[100:101], v234, v0
	v_max_f32_e32 v100, v100, v104
	v_cndmask_b32_e32 v105, v101, v230, vcc
	v_cmp_lt_f32_e32 vcc, v243, v0
	v_max_f32_e32 v100, v100, v105
	v_cndmask_b32_e64 v104, v101, v232, s[98:99]
	v_cmp_lt_f32_e64 s[98:99], v245, v0
	v_max_f32_e32 v100, v100, v104
	v_cndmask_b32_e64 v105, v101, v234, s[100:101]
	v_cmp_lt_f32_e64 s[100:101], v247, v0
	v_max_f32_e32 v100, v100, v105
	v_cndmask_b32_e32 v104, v101, v243, vcc
	v_cmp_lt_f32_e32 vcc, v249, v0
	v_max_f32_e32 v100, v100, v104
	v_cndmask_b32_e64 v105, v101, v245, s[98:99]
	v_cmp_lt_f32_e64 s[98:99], v244, v0
	v_max_f32_e32 v100, v100, v105
	v_cndmask_b32_e64 v104, v101, v247, s[100:101]
	v_cmp_lt_f32_e64 s[100:101], v246, v0
	v_max_f32_e32 v100, v100, v104
	v_cndmask_b32_e32 v105, v101, v249, vcc
	v_cmp_lt_f32_e32 vcc, v248, v0
	v_max_f32_e32 v100, v100, v105
	v_cndmask_b32_e64 v104, v101, v244, s[98:99]
	v_cmp_lt_f32_e64 s[98:99], v250, v0
	v_max_f32_e32 v100, v100, v104
	v_cndmask_b32_e64 v105, v101, v246, s[100:101]
	v_cmp_lt_f32_e64 s[100:101], v219, v0
	v_max_f32_e32 v100, v100, v105
	v_cndmask_b32_e32 v104, v101, v248, vcc
	v_cmp_lt_f32_e32 vcc, v221, v0
	v_max_f32_e32 v100, v100, v104
	v_cndmask_b32_e64 v105, v101, v250, s[98:99]
	v_cmp_lt_f32_e64 s[98:99], v223, v0
	v_max_f32_e32 v100, v100, v105
	v_cndmask_b32_e64 v104, v101, v219, s[100:101]
	v_cmp_lt_f32_e64 s[100:101], v225, v0
	v_max_f32_e32 v100, v100, v104
	v_cndmask_b32_e32 v105, v101, v221, vcc
	v_cmp_lt_f32_e32 vcc, v220, v0
	v_max_f32_e32 v100, v100, v105
	v_cndmask_b32_e64 v104, v101, v223, s[98:99]
	v_cmp_lt_f32_e64 s[98:99], v222, v0
	v_max_f32_e32 v100, v100, v104
	v_cndmask_b32_e64 v105, v101, v225, s[100:101]
	v_cmp_lt_f32_e64 s[100:101], v224, v0
	v_max_f32_e32 v100, v100, v105
	v_cndmask_b32_e32 v104, v101, v220, vcc
	v_cmp_lt_f32_e32 vcc, v226, v0
	v_max_f32_e32 v100, v100, v104
	v_cndmask_b32_e64 v105, v101, v222, s[98:99]
	v_cmp_lt_f32_e64 s[98:99], v235, v0
	v_max_f32_e32 v100, v100, v105
	v_cndmask_b32_e64 v104, v101, v224, s[100:101]
	v_cmp_lt_f32_e64 s[100:101], v237, v0
	v_max_f32_e32 v100, v100, v104
	v_cndmask_b32_e32 v105, v101, v226, vcc
	v_cmp_lt_f32_e32 vcc, v239, v0
	v_max_f32_e32 v100, v100, v105
	v_cndmask_b32_e64 v104, v101, v235, s[98:99]
	v_cmp_lt_f32_e64 s[98:99], v241, v0
	v_max_f32_e32 v100, v100, v104
	v_cndmask_b32_e64 v105, v101, v237, s[100:101]
	v_cmp_lt_f32_e64 s[100:101], v236, v0
	v_max_f32_e32 v100, v100, v105
	v_cndmask_b32_e32 v104, v101, v239, vcc
	v_cmp_lt_f32_e32 vcc, v238, v0
	v_max_f32_e32 v100, v100, v104
	v_cndmask_b32_e64 v105, v101, v241, s[98:99]
	v_cmp_lt_f32_e64 s[98:99], v240, v0
	v_max_f32_e32 v100, v100, v105
	v_cndmask_b32_e64 v104, v101, v236, s[100:101]
	v_cmp_lt_f32_e64 s[100:101], v242, v0
	v_max_f32_e32 v100, v100, v104
	v_cndmask_b32_e32 v105, v101, v238, vcc
	v_cmp_lt_f32_e32 vcc, v251, v0
	v_max_f32_e32 v100, v100, v105
	v_cndmask_b32_e64 v104, v101, v240, s[98:99]
	v_cmp_lt_f32_e64 s[98:99], v253, v0
	v_max_f32_e32 v100, v100, v104
	v_cndmask_b32_e64 v105, v101, v242, s[100:101]
	v_cmp_lt_f32_e64 s[100:101], v133, v0
	v_max_f32_e32 v100, v100, v105
	v_cndmask_b32_e32 v104, v101, v251, vcc
	v_cmp_lt_f32_e32 vcc, v80, v0
	v_max_f32_e32 v100, v100, v104
	v_cndmask_b32_e64 v105, v101, v253, s[98:99]
	v_cmp_lt_f32_e64 s[98:99], v252, v0
	v_max_f32_e32 v100, v100, v105
	v_cndmask_b32_e64 v104, v101, v133, s[100:101]
	v_cmp_lt_f32_e64 s[100:101], v215, v0
	v_max_f32_e32 v100, v100, v104
	v_cndmask_b32_e32 v105, v101, v80, vcc
	v_cmp_lt_f32_e32 vcc, v84, v0
	v_max_f32_e32 v100, v100, v105
	v_cndmask_b32_e64 v104, v101, v252, s[98:99]
	v_cmp_lt_f32_e64 s[98:99], v16, v0
	v_max_f32_e32 v100, v100, v104
	v_cndmask_b32_e64 v105, v101, v215, s[100:101]
	v_max_f32_e32 v100, v100, v105
	v_cndmask_b32_e32 v104, v101, v84, vcc
	v_max_f32_e32 v100, v100, v104
	v_cndmask_b32_e64 v105, v101, v16, s[98:99]
	v_max_f32_e32 v100, v100, v105
	s_nop 1
	v_max_f32_dpp v100, v100, v100 quad_perm:[1,0,3,2] row_mask:0xf bank_mask:0xf
	s_nop 1
	v_max_f32_dpp v100, v100, v100 quad_perm:[2,3,0,1] row_mask:0xf bank_mask:0xf
	s_nop 1
	v_max_f32_dpp v100, v100, v100 row_half_mirror row_mask:0xf bank_mask:0xf
	s_nop 1
	v_max_f32_dpp v100, v100, v100 row_mirror row_mask:0xf bank_mask:0xf
	s_nop 1
	v_max_f32_dpp v100, v100, v100 row_bcast:15 row_mask:0xa bank_mask:0xf
	s_nop 0
	v_readlane_b32 s98, v100, 31
	v_readlane_b32 s99, v100, 63
	s_nop 1
	v_mov_b32_e32 v102, s99
	v_mov_b32_e32 v103, s98
	v_cndmask_b32_e64 v102, v102, v103, s[6:7]
	v_cndmask_b32_e64 v6, v6, v102, s[82:83]
	s_or_b64 s[72:73], s[72:73], s[82:83]
	s_branch .Lwalkret0

.LBB0_2136:
	s_nop 1
	v_add_u32_dpp v7, v7, v7 quad_perm:[1,0,3,2] row_mask:0xf bank_mask:0xf bound_ctrl:1
	s_nop 1
	v_add_u32_dpp v7, v7, v7 quad_perm:[2,3,0,1] row_mask:0xf bank_mask:0xf bound_ctrl:1
	s_nop 1
	v_add_u32_dpp v7, v7, v7 row_half_mirror row_mask:0xf bank_mask:0xf bound_ctrl:1
	s_nop 1
	v_add_u32_dpp v7, v7, v7 row_mirror row_mask:0xf bank_mask:0xf bound_ctrl:1
	s_nop 1
	v_add_u32_dpp v7, v7, v7 row_bcast:15 row_mask:0xa bank_mask:0xf
	s_nop 0
	v_readlane_b32 s0, v7, 31
	v_readlane_b32 s1, v7, 63
	s_nop 1
	v_mov_b32_e32 v7, s1
	v_mov_b32_e32 v8, s0
	v_cndmask_b32_e64 v8, v7, v8, s[8:9]
	v_cmp_lt_i32_e64 s[82:83], s33, v8
	v_cmp_eq_u32_e64 s[84:85], s33, v8
	v_cvt_f32_i32_e32 v8, v8
	s_andn2_b64 s[84:85], s[84:85], s[74:75]
	s_nop 0
	v_cndmask_b32_e64 v6, v6, v0, s[84:85]
	s_or_b64 s[84:85], s[84:85], s[74:75]
	s_andn2_b64 s[86:87], s[82:83], s[84:85]
	s_or_b64 s[88:89], s[82:83], s[84:85]
	s_andn2_b64 s[88:89], exec, s[88:89]
	v_cndmask_b32_e64 v4, v4, v0, s[86:87]
	v_cndmask_b32_e64 v3, v3, v8, s[86:87]
	v_cndmask_b32_e64 v5, v5, v0, s[88:89]
	v_cndmask_b32_e64 v2, v2, v8, s[88:89]
	s_or_b64 s[80:81], s[80:81], s[86:87]
	s_or_b64 s[78:79], s[78:79], s[88:89]
	s_and_b64 s[90:91], s[80:81], s[78:79]
	v_sub_f32_e32 v9, v3, v2
	v_rcp_f32_e32 v9, v9
	v_add_f32_e32 v10, 0xc3800000, v3
	s_and_b32 s98, s60, 3
	s_cmp_lg_u32 s98, 3
	s_cselect_b64 vcc, -1, 0
	v_mul_f32_e32 v9, v10, v9
	v_max_f32_e32 v9, 0x3ca3d70a, v9
	v_min_f32_e32 v9, 0x3f7ae148, v9
	v_cndmask_b32_e32 v9, 0.5, v9, vcc
	v_sub_f32_e32 v10, v5, v4
	v_fma_f32 v10, v10, v9, v4
	v_mul_f32_e32 v11, 0.5, v5
	v_fmac_f32_e32 v11, 0.5, v4
	v_cmp_ngt_f32_e32 vcc, v10, v4
	v_cmp_nlt_f32_e64 s[98:99], v10, v5
	v_cmp_ngt_f32_e64 s[100:101], v11, v4
	s_or_b64 s[98:99], vcc, s[98:99]
	v_cmp_nlt_f32_e32 vcc, v11, v5
	s_nop 0
	v_cndmask_b32_e64 v10, v10, v11, s[98:99]
	s_or_b64 s[100:101], vcc, s[100:101]
	s_and_b64 s[100:101], s[100:101], s[98:99]
	s_and_b64 s[100:101], s[100:101], s[90:91]
	s_andn2_b64 s[100:101], s[100:101], s[84:85]
	v_cndmask_b32_e64 v11, -v1, v1, s[82:83]
	v_add_f32_e32 v11, v0, v11
	v_cndmask_b32_e64 v10, v11, v10, s[90:91]
	v_add_f32_e32 v11, v1, v1
	s_or_b64 s[98:99], s[90:91], s[84:85]
	s_andn2_b64 s[98:99], exec, s[98:99]
	v_cndmask_b32_e64 v1, v1, v11, s[98:99]
	v_cndmask_b32_e64 v6, v6, v4, s[100:101]
	s_or_b64 s[74:75], s[84:85], s[100:101]
	s_mov_b32 s98, 0x437f0000
	v_cmp_eq_f32_e64 s[82:83], s98, v8
	s_andn2_b64 s[82:83], s[82:83], s[74:75]
	s_cmp_lg_u64 s[82:83], 0
	s_cbranch_scc1 .Lwalk1
.Lwalkret1:
	s_andn2_b64 s[98:99], exec, s[74:75]
	v_cndmask_b32_e64 v0, v0, v10, s[98:99]
	s_cmp_eq_u64 s[98:99], 0
	s_cbranch_scc1 .Ldx1
	s_cmp_eq_u32 s60, 63
	s_cbranch_scc1 .Ldx1
	s_add_i32 s60, s60, 1
	s_branch .LBB0_2124
.Lwalk1:
	v_mov_b32_e32 v100, 0xff800000
	v_mov_b32_e32 v101, 0xff800000
	v_cmp_lt_f32_e64 s[98:99], v201, v0
	v_cmp_lt_f32_e64 s[100:101], v209, v0
	v_cmp_lt_f32_e32 vcc, v200, v0
	v_cndmask_b32_e64 v104, v101, v201, s[98:99]
	v_cmp_lt_f32_e64 s[98:99], v202, v0
	v_max_f32_e32 v100, v100, v104
	v_cndmask_b32_e64 v105, v101, v209, s[100:101]
	v_cmp_lt_f32_e64 s[100:101], v112, v0
	v_max_f32_e32 v100, v100, v105
	v_cndmask_b32_e32 v104, v101, v200, vcc
	v_cmp_lt_f32_e32 vcc, v113, v0
	v_max_f32_e32 v100, v100, v104
	v_cndmask_b32_e64 v105, v101, v202, s[98:99]
	v_cmp_lt_f32_e64 s[98:99], v114, v0
	v_max_f32_e32 v100, v100, v105
	v_cndmask_b32_e64 v104, v101, v112, s[100:101]
	v_cmp_lt_f32_e64 s[100:101], v115, v0
	v_max_f32_e32 v100, v100, v104
	v_cndmask_b32_e32 v105, v101, v113, vcc
	v_cmp_lt_f32_e32 vcc, v116, v0
	v_max_f32_e32 v100, v100, v105
	v_cndmask_b32_e64 v104, v101, v114, s[98:99]
	v_cmp_lt_f32_e64 s[98:99], v117, v0
	v_max_f32_e32 v100, v100, v104
	v_cndmask_b32_e64 v105, v101, v115, s[100:101]
	v_cmp_lt_f32_e64 s[100:101], v118, v0
	v_max_f32_e32 v100, v100, v105
	v_cndmask_b32_e32 v104, v101, v116, vcc
	v_cmp_lt_f32_e32 vcc, v119, v0
	v_max_f32_e32 v100, v100, v104
	v_cndmask_b32_e64 v105, v101, v117, s[98:99]
	v_cmp_lt_f32_e64 s[98:99], v205, v0
	v_max_f32_e32 v100, v100, v105
	v_cndmask_b32_e64 v104, v101, v118, s[100:101]
	v_cmp_lt_f32_e64 s[100:101], v206, v0
	v_max_f32_e32 v100, v100, v104
	v_cndmask_b32_e32 v105, v101, v119, vcc
	v_cmp_lt_f32_e32 vcc, v207, v0
	v_max_f32_e32 v100, v100, v105
	v_cndmask_b32_e64 v104, v101, v205, s[98:99]
	v_cmp_lt_f32_e64 s[98:99], v208, v0
	v_max_f32_e32 v100, v100, v104
	v_cndmask_b32_e64 v105, v101, v206, s[100:101]
	v_cmp_lt_f32_e64 s[100:101], v210, v0
	v_max_f32_e32 v100, v100, v105
	v_cndmask_b32_e32 v104, v101, v207, vcc
	v_cmp_lt_f32_e32 vcc, v212, v0
	v_max_f32_e32 v100, v100, v104
	v_cndmask_b32_e64 v105, v101, v208, s[98:99]
	v_cmp_lt_f32_e64 s[98:99], v214, v0
	v_max_f32_e32 v100, v100, v105
	v_cndmask_b32_e64 v104, v101, v210, s[100:101]
	v_cmp_lt_f32_e64 s[100:101], v217, v0
	v_max_f32_e32 v100, v100, v104
	v_cndmask_b32_e32 v105, v101, v212, vcc
	v_cmp_lt_f32_e32 vcc, v211, v0
	v_max_f32_e32 v100, v100, v105
	v_cndmask_b32_e64 v104, v101, v214, s[98:99]
	v_cmp_lt_f32_e64 s[98:99], v213, v0
	v_max_f32_e32 v100, v100, v104
	v_cndmask_b32_e64 v105, v101, v217, s[100:101]
	v_cmp_lt_f32_e64 s[100:101], v216, v0
	v_max_f32_e32 v100, v100, v105
	v_cndmask_b32_e32 v104, v101, v211, vcc
	v_cmp_lt_f32_e32 vcc, v218, v0
	v_max_f32_e32 v100, v100, v104
	v_cndmask_b32_e64 v105, v101, v213, s[98:99]
	v_cmp_lt_f32_e64 s[98:99], v227, v0
	v_max_f32_e32 v100, v100, v105
	v_cndmask_b32_e64 v104, v101, v216, s[100:101]
	v_cmp_lt_f32_e64 s[100:101], v229, v0
	v_max_f32_e32 v100, v100, v104
	v_cndmask_b32_e32 v105, v101, v218, vcc
	v_cmp_lt_f32_e32 vcc, v231, v0
	v_max_f32_e32 v100, v100, v105
	v_cndmask_b32_e64 v104, v101, v227, s[98:99]
	v_cmp_lt_f32_e64 s[98:99], v233, v0
	v_max_f32_e32 v100, v100, v104
	v_cndmask_b32_e64 v105, v101, v229, s[100:101]
	v_cmp_lt_f32_e64 s[100:101], v228, v0
	v_max_f32_e32 v100, v100, v105
	v_cndmask_b32_e32 v104, v101, v231, vcc
	v_cmp_lt_f32_e32 vcc, v230, v0
	v_max_f32_e32 v100, v100, v104
	v_cndmask_b32_e64 v105, v101, v233, s[98:99]
	v_cmp_lt_f32_e64 s[98:99], v232, v0
	v_max_f32_e32 v100, v100, v105
	v_cndmask_b32_e64 v104, v101, v228, s[100:101]
	v_cmp_lt_f32_e64 s[100:101], v234, v0
	v_max_f32_e32 v100, v100, v104
	v_cndmask_b32_e32 v105, v101, v230, vcc
	v_cmp_lt_f32_e32 vcc, v243, v0
	v_max_f32_e32 v100, v100, v105
	v_cndmask_b32_e64 v104, v101, v232, s[98:99]
	v_cmp_lt_f32_e64 s[98:99], v245, v0
	v_max_f32_e32 v100, v100, v104
	v_cndmask_b32_e64 v105, v101, v234, s[100:101]
	v_cmp_lt_f32_e64 s[100:101], v247, v0
	v_max_f32_e32 v100, v100, v105
	v_cndmask_b32_e32 v104, v101, v243, vcc
	v_cmp_lt_f32_e32 vcc, v249, v0
	v_max_f32_e32 v100, v100, v104
	v_cndmask_b32_e64 v105, v101, v245, s[98:99]
	v_cmp_lt_f32_e64 s[98:99], v244, v0
	v_max_f32_e32 v100, v100, v105
	v_cndmask_b32_e64 v104, v101, v247, s[100:101]
	v_cmp_lt_f32_e64 s[100:101], v246, v0
	v_max_f32_e32 v100, v100, v104
	v_cndmask_b32_e32 v105, v101, v249, vcc
	v_cmp_lt_f32_e32 vcc, v248, v0
	v_max_f32_e32 v100, v100, v105
	v_cndmask_b32_e64 v104, v101, v244, s[98:99]
	v_cmp_lt_f32_e64 s[98:99], v250, v0
	v_max_f32_e32 v100, v100, v104
	v_cndmask_b32_e64 v105, v101, v246, s[100:101]
	v_cmp_lt_f32_e64 s[100:101], v219, v0
	v_max_f32_e32 v100, v100, v105
	v_cndmask_b32_e32 v104, v101, v248, vcc
	v_cmp_lt_f32_e32 vcc, v221, v0
	v_max_f32_e32 v100, v100, v104
	v_cndmask_b32_e64 v105, v101, v250, s[98:99]
	v_cmp_lt_f32_e64 s[98:99], v223, v0
	v_max_f32_e32 v100, v100, v105
	v_cndmask_b32_e64 v104, v101, v219, s[100:101]
	v_cmp_lt_f32_e64 s[100:101], v225, v0
	v_max_f32_e32 v100, v100, v104
	v_cndmask_b32_e32 v105, v101, v221, vcc
	v_cmp_lt_f32_e32 vcc, v220, v0
	v_max_f32_e32 v100, v100, v105
	v_cndmask_b32_e64 v104, v101, v223, s[98:99]
	v_cmp_lt_f32_e64 s[98:99], v222, v0
	v_max_f32_e32 v100, v100, v104
	v_cndmask_b32_e64 v105, v101, v225, s[100:101]
	v_cmp_lt_f32_e64 s[100:101], v224, v0
	v_max_f32_e32 v100, v100, v105
	v_cndmask_b32_e32 v104, v101, v220, vcc
	v_cmp_lt_f32_e32 vcc, v226, v0
	v_max_f32_e32 v100, v100, v104
	v_cndmask_b32_e64 v105, v101, v222, s[98:99]
	v_cmp_lt_f32_e64 s[98:99], v235, v0
	v_max_f32_e32 v100, v100, v105
	v_cndmask_b32_e64 v104, v101, v224, s[100:101]
	v_cmp_lt_f32_e64 s[100:101], v237, v0
	v_max_f32_e32 v100, v100, v104
	v_cndmask_b32_e32 v105, v101, v226, vcc
	v_cmp_lt_f32_e32 vcc, v239, v0
	v_max_f32_e32 v100, v100, v105
	v_cndmask_b32_e64 v104, v101, v235, s[98:99]
	v_cmp_lt_f32_e64 s[98:99], v241, v0
	v_max_f32_e32 v100, v100, v104
	v_cndmask_b32_e64 v105, v101, v237, s[100:101]
	v_cmp_lt_f32_e64 s[100:101], v236, v0
	v_max_f32_e32 v100, v100, v105
	v_cndmask_b32_e32 v104, v101, v239, vcc
	v_cmp_lt_f32_e32 vcc, v238, v0
	v_max_f32_e32 v100, v100, v104
	v_cndmask_b32_e64 v105, v101, v241, s[98:99]
	v_cmp_lt_f32_e64 s[98:99], v240, v0
	v_max_f32_e32 v100, v100, v105
	v_cndmask_b32_e64 v104, v101, v236, s[100:101]
	v_cmp_lt_f32_e64 s[100:101], v242, v0
	v_max_f32_e32 v100, v100, v104
	v_cndmask_b32_e32 v105, v101, v238, vcc
	v_cmp_lt_f32_e32 vcc, v251, v0
	v_max_f32_e32 v100, v100, v105
	v_cndmask_b32_e64 v104, v101, v240, s[98:99]
	v_cmp_lt_f32_e64 s[98:99], v253, v0
	v_max_f32_e32 v100, v100, v104
	v_cndmask_b32_e64 v105, v101, v242, s[100:101]
	v_cmp_lt_f32_e64 s[100:101], v133, v0
	v_max_f32_e32 v100, v100, v105
	v_cndmask_b32_e32 v104, v101, v251, vcc
	v_cmp_lt_f32_e32 vcc, v80, v0
	v_max_f32_e32 v100, v100, v104
	v_cndmask_b32_e64 v105, v101, v253, s[98:99]
	v_cmp_lt_f32_e64 s[98:99], v252, v0
	v_max_f32_e32 v100, v100, v105
	v_cndmask_b32_e64 v104, v101, v133, s[100:101]
	v_cmp_lt_f32_e64 s[100:101], v215, v0
	v_max_f32_e32 v100, v100, v104
	v_cndmask_b32_e32 v105, v101, v80, vcc
	v_cmp_lt_f32_e32 vcc, v84, v0
	v_max_f32_e32 v100, v100, v105
	v_cndmask_b32_e64 v104, v101, v252, s[98:99]
	v_cmp_lt_f32_e64 s[98:99], v16, v0
	v_max_f32_e32 v100, v100, v104
	v_cndmask_b32_e64 v105, v101, v215, s[100:101]
	v_max_f32_e32 v100, v100, v105
	v_cndmask_b32_e32 v104, v101, v84, vcc
	v_max_f32_e32 v100, v100, v104
	v_cndmask_b32_e64 v105, v101, v16, s[98:99]
	v_max_f32_e32 v100, v100, v105
	s_nop 1
	v_max_f32_dpp v100, v100, v100 quad_perm:[1,0,3,2] row_mask:0xf bank_mask:0xf
	s_nop 1
	v_max_f32_dpp v100, v100, v100 quad_perm:[2,3,0,1] row_mask:0xf bank_mask:0xf
	s_nop 1
	v_max_f32_dpp v100, v100, v100 row_half_mirror row_mask:0xf bank_mask:0xf
	s_nop 1
	v_max_f32_dpp v100, v100, v100 row_mirror row_mask:0xf bank_mask:0xf
	s_nop 1
	v_max_f32_dpp v100, v100, v100 row_bcast:15 row_mask:0xa bank_mask:0xf
	s_nop 0
	v_readlane_b32 s98, v100, 31
	v_readlane_b32 s99, v100, 63
	s_nop 1
	v_mov_b32_e32 v102, s99
	v_mov_b32_e32 v103, s98
	v_cndmask_b32_e64 v102, v102, v103, s[8:9]
	v_cndmask_b32_e64 v6, v6, v102, s[82:83]
	s_or_b64 s[74:75], s[74:75], s[82:83]
	s_branch .Lwalkret1
